# forget-logit job K loop restaged through LDS by LDS-DMA (x rows wave-private double-buffered, weight block shared, xor-swizzled), same bf16 MFMA sequence
# speedup vs baseline: 1.1075x; 1.0201x over previous
.LBB0_485:
	v_mov_b32_e32 v2, 0
	v_mov_b32_e32 v3, 0
	v_mov_b32_e32 v4, 0
	v_mov_b32_e32 v5, 0
	v_readfirstlane_b32 s6, v25
	s_mov_b32 s13, m0
	v_and_b32_e32 v29, 63, v182
	v_lshrrev_b32_e32 v30, 4, v29
	v_and_b32_e32 v31, 15, v29
	v_xor_b32_e32 v32, v31, v30
	v_lshlrev_b32_e32 v33, 11, v30
	v_xor_b32_e32 v0, 0, v32
	v_lshl_add_u32 v90, v0, 4, v33
	v_xor_b32_e32 v0, 4, v32
	v_lshl_add_u32 v91, v0, 4, v33
	v_xor_b32_e32 v0, 8, v32
	v_lshl_add_u32 v92, v0, 4, v33
	v_xor_b32_e32 v0, 12, v32
	v_lshl_add_u32 v93, v0, 4, v33
	s_lshr_b32 s7, s6, 4
	s_lshl_b32 s8, s4, 7
	s_add_i32 s8, s8, s6
	s_lshl_b32 s8, s8, 11
	s_add_u32 s10, s70, 0x2448000
	s_addc_u32 s11, s71, 0
	s_add_u32 s10, s10, s8
	s_addc_u32 s11, s11, 0
	s_lshl_b32 s12, s7, 13
	v_lshlrev_b32_e32 v33, 8, v31
	v_add_u32_e32 v33, s12, v33
	v_or_b32_e32 v0, 0, v30
	v_xor_b32_e32 v0, v0, v31
	v_lshl_add_u32 v34, v0, 4, v33
	v_or_b32_e32 v0, 4, v30
	v_xor_b32_e32 v0, v0, v31
	v_lshl_add_u32 v35, v0, 4, v33
	v_or_b32_e32 v0, 8, v30
	v_xor_b32_e32 v0, v0, v31
	v_lshl_add_u32 v36, v0, 4, v33
	v_or_b32_e32 v0, 12, v30
	v_xor_b32_e32 v0, v0, v31
	v_lshl_add_u32 v37, v0, 4, v33
	v_lshlrev_b32_e32 v33, 11, v31
	v_add_u32_e32 v33, 0x10000, v33
	v_or_b32_e32 v0, 0, v30
	v_xor_b32_e32 v0, v0, v31
	v_lshl_add_u32 v38, v0, 4, v33
	v_or_b32_e32 v0, 4, v30
	v_xor_b32_e32 v0, v0, v31
	v_lshl_add_u32 v39, v0, 4, v33
	v_or_b32_e32 v0, 8, v30
	v_xor_b32_e32 v0, v0, v31
	v_lshl_add_u32 v40, v0, 4, v33
	v_or_b32_e32 v0, 12, v30
	v_xor_b32_e32 v0, v0, v31
	v_lshl_add_u32 v41, v0, 4, v33
	v_readlane_b32 s0, v251, 49
	v_readlane_b32 s1, v251, 50
	s_lshl_b32 s8, s16, 15
	s_sub_u32 s0, s0, 0x200
	s_subb_u32 s1, s1, 0
	s_add_u32 s0, s0, s8
	s_addc_u32 s1, s1, 0
	s_lshl_b32 s8, s7, 1
	v_xor_b32_e32 v0, s8, v29
	v_lshlrev_b32_e32 v0, 4, v0
	s_lshl_b32 s9, s8, 11
	s_add_i32 s9, s9, 0x0
	v_add_u32_e32 v0, s9, v0
	v_lshl_add_u64 v[94:95], s[0:1], 0, v[0:1]
	s_add_i32 s9, s9, 0x10000
	s_mov_b32 m0, s9
	s_nop 0
	global_load_lds_dwordx4 v[94:95], off
	s_lshl_b32 s8, s7, 1
	v_xor_b32_e32 v0, s8, v29
	v_lshlrev_b32_e32 v0, 4, v0
	s_lshl_b32 s9, s8, 11
	s_add_i32 s9, s9, 0x400
	v_add_u32_e32 v0, s9, v0
	v_lshl_add_u64 v[94:95], s[0:1], 0, v[0:1]
	s_add_i32 s9, s9, 0x10000
	s_mov_b32 m0, s9
	s_nop 0
	global_load_lds_dwordx4 v[94:95], off
	s_lshl_b32 s8, s7, 1
	s_add_i32 s8, s8, 1
	v_xor_b32_e32 v0, s8, v29
	v_lshlrev_b32_e32 v0, 4, v0
	s_lshl_b32 s9, s8, 11
	s_add_i32 s9, s9, 0x0
	v_add_u32_e32 v0, s9, v0
	v_lshl_add_u64 v[94:95], s[0:1], 0, v[0:1]
	s_add_i32 s9, s9, 0x10000
	s_mov_b32 m0, s9
	s_nop 0
	global_load_lds_dwordx4 v[94:95], off
	s_lshl_b32 s8, s7, 1
	s_add_i32 s8, s8, 1
	v_xor_b32_e32 v0, s8, v29
	v_lshlrev_b32_e32 v0, 4, v0
	s_lshl_b32 s9, s8, 11
	s_add_i32 s9, s9, 0x400
	v_add_u32_e32 v0, s9, v0
	v_lshl_add_u64 v[94:95], s[0:1], 0, v[0:1]
	s_add_i32 s9, s9, 0x10000
	s_mov_b32 m0, s9
	s_nop 0
	global_load_lds_dwordx4 v[94:95], off
	s_add_u32 s8, s10, 0x0
	s_addc_u32 s9, s11, 0
	v_mov_b32_e32 v0, v90
	v_lshl_add_u64 v[94:95], s[8:9], 0, v[0:1]
	s_add_i32 s8, s12, 0x0
	s_mov_b32 m0, s8
	s_nop 0
	global_load_lds_dwordx4 v[94:95], off
	s_add_u32 s8, s10, 0x2000
	s_addc_u32 s9, s11, 0
	v_mov_b32_e32 v0, v91
	v_lshl_add_u64 v[94:95], s[8:9], 0, v[0:1]
	s_add_i32 s8, s12, 0x400
	s_mov_b32 m0, s8
	s_nop 0
	global_load_lds_dwordx4 v[94:95], off
	s_add_u32 s8, s10, 0x4000
	s_addc_u32 s9, s11, 0
	v_mov_b32_e32 v0, v92
	v_lshl_add_u64 v[94:95], s[8:9], 0, v[0:1]
	s_add_i32 s8, s12, 0x800
	s_mov_b32 m0, s8
	s_nop 0
	global_load_lds_dwordx4 v[94:95], off
	s_add_u32 s8, s10, 0x6000
	s_addc_u32 s9, s11, 0
	v_mov_b32_e32 v0, v93
	v_lshl_add_u64 v[94:95], s[8:9], 0, v[0:1]
	s_add_i32 s8, s12, 0xc00
	s_mov_b32 m0, s8
	s_nop 0
	global_load_lds_dwordx4 v[94:95], off
	s_add_u32 s8, s10, 0x100
	s_addc_u32 s9, s11, 0
	v_mov_b32_e32 v0, v90
	v_lshl_add_u64 v[94:95], s[8:9], 0, v[0:1]
	s_add_i32 s8, s12, 0x1000
	s_mov_b32 m0, s8
	s_nop 0
	global_load_lds_dwordx4 v[94:95], off
	s_add_u32 s8, s10, 0x2100
	s_addc_u32 s9, s11, 0
	v_mov_b32_e32 v0, v91
	v_lshl_add_u64 v[94:95], s[8:9], 0, v[0:1]
	s_add_i32 s8, s12, 0x1400
	s_mov_b32 m0, s8
	s_nop 0
	global_load_lds_dwordx4 v[94:95], off
	s_add_u32 s8, s10, 0x4100
	s_addc_u32 s9, s11, 0
	v_mov_b32_e32 v0, v92
	v_lshl_add_u64 v[94:95], s[8:9], 0, v[0:1]
	s_add_i32 s8, s12, 0x1800
	s_mov_b32 m0, s8
	s_nop 0
	global_load_lds_dwordx4 v[94:95], off
	s_add_u32 s8, s10, 0x6100
	s_addc_u32 s9, s11, 0
	v_mov_b32_e32 v0, v93
	v_lshl_add_u64 v[94:95], s[8:9], 0, v[0:1]
	s_add_i32 s8, s12, 0x1c00
	s_mov_b32 m0, s8
	s_nop 0
	global_load_lds_dwordx4 v[94:95], off
	s_waitcnt vmcnt(8)
	s_barrier
	s_waitcnt vmcnt(4)
	ds_read_b128 v[74:77], v34 offset:0
	ds_read_b128 v[42:45], v38 offset:0
	ds_read_b128 v[78:81], v35 offset:0
	ds_read_b128 v[46:49], v39 offset:0
	ds_read_b128 v[82:85], v36 offset:0
	ds_read_b128 v[50:53], v40 offset:0
	ds_read_b128 v[86:89], v37 offset:0
	ds_read_b128 v[54:57], v41 offset:0
	s_waitcnt lgkmcnt(0)
	s_add_u32 s8, s10, 0x200
	s_addc_u32 s9, s11, 0
	v_mov_b32_e32 v0, v90
	v_lshl_add_u64 v[94:95], s[8:9], 0, v[0:1]
	s_add_i32 s8, s12, 0x0
	s_mov_b32 m0, s8
	s_nop 0
	global_load_lds_dwordx4 v[94:95], off
	s_add_u32 s8, s10, 0x2200
	s_addc_u32 s9, s11, 0
	v_mov_b32_e32 v0, v91
	v_lshl_add_u64 v[94:95], s[8:9], 0, v[0:1]
	s_add_i32 s8, s12, 0x400
	s_mov_b32 m0, s8
	s_nop 0
	global_load_lds_dwordx4 v[94:95], off
	s_add_u32 s8, s10, 0x4200
	s_addc_u32 s9, s11, 0
	v_mov_b32_e32 v0, v92
	v_lshl_add_u64 v[94:95], s[8:9], 0, v[0:1]
	s_add_i32 s8, s12, 0x800
	s_mov_b32 m0, s8
	s_nop 0
	global_load_lds_dwordx4 v[94:95], off
	s_add_u32 s8, s10, 0x6200
	s_addc_u32 s9, s11, 0
	v_mov_b32_e32 v0, v93
	v_lshl_add_u64 v[94:95], s[8:9], 0, v[0:1]
	s_add_i32 s8, s12, 0xc00
	s_mov_b32 m0, s8
	s_nop 0
	global_load_lds_dwordx4 v[94:95], off
	v_mfma_f32_16x16x32_bf16 v[2:5], v[42:45], v[74:77], v[2:5]
	v_mfma_f32_16x16x32_bf16 v[2:5], v[46:49], v[78:81], v[2:5]
	v_mfma_f32_16x16x32_bf16 v[2:5], v[50:53], v[82:85], v[2:5]
	v_mfma_f32_16x16x32_bf16 v[2:5], v[54:57], v[86:89], v[2:5]
	s_waitcnt vmcnt(4)
	ds_read_b128 v[74:77], v34 offset:4096
	ds_read_b128 v[42:45], v38 offset:256
	ds_read_b128 v[78:81], v35 offset:4096
	ds_read_b128 v[46:49], v39 offset:256
	ds_read_b128 v[82:85], v36 offset:4096
	ds_read_b128 v[50:53], v40 offset:256
	ds_read_b128 v[86:89], v37 offset:4096
	ds_read_b128 v[54:57], v41 offset:256
	s_waitcnt lgkmcnt(0)
	s_add_u32 s8, s10, 0x300
	s_addc_u32 s9, s11, 0
	v_mov_b32_e32 v0, v90
	v_lshl_add_u64 v[94:95], s[8:9], 0, v[0:1]
	s_add_i32 s8, s12, 0x1000
	s_mov_b32 m0, s8
	s_nop 0
	global_load_lds_dwordx4 v[94:95], off
	s_add_u32 s8, s10, 0x2300
	s_addc_u32 s9, s11, 0
	v_mov_b32_e32 v0, v91
	v_lshl_add_u64 v[94:95], s[8:9], 0, v[0:1]
	s_add_i32 s8, s12, 0x1400
	s_mov_b32 m0, s8
	s_nop 0
	global_load_lds_dwordx4 v[94:95], off
	s_add_u32 s8, s10, 0x4300
	s_addc_u32 s9, s11, 0
	v_mov_b32_e32 v0, v92
	v_lshl_add_u64 v[94:95], s[8:9], 0, v[0:1]
	s_add_i32 s8, s12, 0x1800
	s_mov_b32 m0, s8
	s_nop 0
	global_load_lds_dwordx4 v[94:95], off
	s_add_u32 s8, s10, 0x6300
	s_addc_u32 s9, s11, 0
	v_mov_b32_e32 v0, v93
	v_lshl_add_u64 v[94:95], s[8:9], 0, v[0:1]
	s_add_i32 s8, s12, 0x1c00
	s_mov_b32 m0, s8
	s_nop 0
	global_load_lds_dwordx4 v[94:95], off
	v_mfma_f32_16x16x32_bf16 v[2:5], v[42:45], v[74:77], v[2:5]
	v_mfma_f32_16x16x32_bf16 v[2:5], v[46:49], v[78:81], v[2:5]
	v_mfma_f32_16x16x32_bf16 v[2:5], v[50:53], v[82:85], v[2:5]
	v_mfma_f32_16x16x32_bf16 v[2:5], v[54:57], v[86:89], v[2:5]
	s_waitcnt vmcnt(4)
	ds_read_b128 v[74:77], v34 offset:0
	ds_read_b128 v[42:45], v38 offset:512
	ds_read_b128 v[78:81], v35 offset:0
	ds_read_b128 v[46:49], v39 offset:512
	ds_read_b128 v[82:85], v36 offset:0
	ds_read_b128 v[50:53], v40 offset:512
	ds_read_b128 v[86:89], v37 offset:0
	ds_read_b128 v[54:57], v41 offset:512
	s_waitcnt lgkmcnt(0)
	s_add_u32 s8, s10, 0x400
	s_addc_u32 s9, s11, 0
	v_mov_b32_e32 v0, v90
	v_lshl_add_u64 v[94:95], s[8:9], 0, v[0:1]
	s_add_i32 s8, s12, 0x0
	s_mov_b32 m0, s8
	s_nop 0
	global_load_lds_dwordx4 v[94:95], off
	s_add_u32 s8, s10, 0x2400
	s_addc_u32 s9, s11, 0
	v_mov_b32_e32 v0, v91
	v_lshl_add_u64 v[94:95], s[8:9], 0, v[0:1]
	s_add_i32 s8, s12, 0x400
	s_mov_b32 m0, s8
	s_nop 0
	global_load_lds_dwordx4 v[94:95], off
	s_add_u32 s8, s10, 0x4400
	s_addc_u32 s9, s11, 0
	v_mov_b32_e32 v0, v92
	v_lshl_add_u64 v[94:95], s[8:9], 0, v[0:1]
	s_add_i32 s8, s12, 0x800
	s_mov_b32 m0, s8
	s_nop 0
	global_load_lds_dwordx4 v[94:95], off
	s_add_u32 s8, s10, 0x6400
	s_addc_u32 s9, s11, 0
	v_mov_b32_e32 v0, v93
	v_lshl_add_u64 v[94:95], s[8:9], 0, v[0:1]
	s_add_i32 s8, s12, 0xc00
	s_mov_b32 m0, s8
	s_nop 0
	global_load_lds_dwordx4 v[94:95], off
	v_mfma_f32_16x16x32_bf16 v[2:5], v[42:45], v[74:77], v[2:5]
	v_mfma_f32_16x16x32_bf16 v[2:5], v[46:49], v[78:81], v[2:5]
	v_mfma_f32_16x16x32_bf16 v[2:5], v[50:53], v[82:85], v[2:5]
	v_mfma_f32_16x16x32_bf16 v[2:5], v[54:57], v[86:89], v[2:5]
	s_waitcnt vmcnt(4)
	ds_read_b128 v[74:77], v34 offset:4096
	ds_read_b128 v[42:45], v38 offset:768
	ds_read_b128 v[78:81], v35 offset:4096
	ds_read_b128 v[46:49], v39 offset:768
	ds_read_b128 v[82:85], v36 offset:4096
	ds_read_b128 v[50:53], v40 offset:768
	ds_read_b128 v[86:89], v37 offset:4096
	ds_read_b128 v[54:57], v41 offset:768
	s_waitcnt lgkmcnt(0)
	s_add_u32 s8, s10, 0x500
	s_addc_u32 s9, s11, 0
	v_mov_b32_e32 v0, v90
	v_lshl_add_u64 v[94:95], s[8:9], 0, v[0:1]
	s_add_i32 s8, s12, 0x1000
	s_mov_b32 m0, s8
	s_nop 0
	global_load_lds_dwordx4 v[94:95], off
	s_add_u32 s8, s10, 0x2500
	s_addc_u32 s9, s11, 0
	v_mov_b32_e32 v0, v91
	v_lshl_add_u64 v[94:95], s[8:9], 0, v[0:1]
	s_add_i32 s8, s12, 0x1400
	s_mov_b32 m0, s8
	s_nop 0
	global_load_lds_dwordx4 v[94:95], off
	s_add_u32 s8, s10, 0x4500
	s_addc_u32 s9, s11, 0
	v_mov_b32_e32 v0, v92
	v_lshl_add_u64 v[94:95], s[8:9], 0, v[0:1]
	s_add_i32 s8, s12, 0x1800
	s_mov_b32 m0, s8
	s_nop 0
	global_load_lds_dwordx4 v[94:95], off
	s_add_u32 s8, s10, 0x6500
	s_addc_u32 s9, s11, 0
	v_mov_b32_e32 v0, v93
	v_lshl_add_u64 v[94:95], s[8:9], 0, v[0:1]
	s_add_i32 s8, s12, 0x1c00
	s_mov_b32 m0, s8
	s_nop 0
	global_load_lds_dwordx4 v[94:95], off
	v_mfma_f32_16x16x32_bf16 v[2:5], v[42:45], v[74:77], v[2:5]
	v_mfma_f32_16x16x32_bf16 v[2:5], v[46:49], v[78:81], v[2:5]
	v_mfma_f32_16x16x32_bf16 v[2:5], v[50:53], v[82:85], v[2:5]
	v_mfma_f32_16x16x32_bf16 v[2:5], v[54:57], v[86:89], v[2:5]
	s_waitcnt vmcnt(4)
	ds_read_b128 v[74:77], v34 offset:0
	ds_read_b128 v[42:45], v38 offset:1024
	ds_read_b128 v[78:81], v35 offset:0
	ds_read_b128 v[46:49], v39 offset:1024
	ds_read_b128 v[82:85], v36 offset:0
	ds_read_b128 v[50:53], v40 offset:1024
	ds_read_b128 v[86:89], v37 offset:0
	ds_read_b128 v[54:57], v41 offset:1024
	s_waitcnt lgkmcnt(0)
	s_add_u32 s8, s10, 0x600
	s_addc_u32 s9, s11, 0
	v_mov_b32_e32 v0, v90
	v_lshl_add_u64 v[94:95], s[8:9], 0, v[0:1]
	s_add_i32 s8, s12, 0x0
	s_mov_b32 m0, s8
	s_nop 0
	global_load_lds_dwordx4 v[94:95], off
	s_add_u32 s8, s10, 0x2600
	s_addc_u32 s9, s11, 0
	v_mov_b32_e32 v0, v91
	v_lshl_add_u64 v[94:95], s[8:9], 0, v[0:1]
	s_add_i32 s8, s12, 0x400
	s_mov_b32 m0, s8
	s_nop 0
	global_load_lds_dwordx4 v[94:95], off
	s_add_u32 s8, s10, 0x4600
	s_addc_u32 s9, s11, 0
	v_mov_b32_e32 v0, v92
	v_lshl_add_u64 v[94:95], s[8:9], 0, v[0:1]
	s_add_i32 s8, s12, 0x800
	s_mov_b32 m0, s8
	s_nop 0
	global_load_lds_dwordx4 v[94:95], off
	s_add_u32 s8, s10, 0x6600
	s_addc_u32 s9, s11, 0
	v_mov_b32_e32 v0, v93
	v_lshl_add_u64 v[94:95], s[8:9], 0, v[0:1]
	s_add_i32 s8, s12, 0xc00
	s_mov_b32 m0, s8
	s_nop 0
	global_load_lds_dwordx4 v[94:95], off
	v_mfma_f32_16x16x32_bf16 v[2:5], v[42:45], v[74:77], v[2:5]
	v_mfma_f32_16x16x32_bf16 v[2:5], v[46:49], v[78:81], v[2:5]
	v_mfma_f32_16x16x32_bf16 v[2:5], v[50:53], v[82:85], v[2:5]
	v_mfma_f32_16x16x32_bf16 v[2:5], v[54:57], v[86:89], v[2:5]
	s_waitcnt vmcnt(4)
	ds_read_b128 v[74:77], v34 offset:4096
	ds_read_b128 v[42:45], v38 offset:1280
	ds_read_b128 v[78:81], v35 offset:4096
	ds_read_b128 v[46:49], v39 offset:1280
	ds_read_b128 v[82:85], v36 offset:4096
	ds_read_b128 v[50:53], v40 offset:1280
	ds_read_b128 v[86:89], v37 offset:4096
	ds_read_b128 v[54:57], v41 offset:1280
	s_waitcnt lgkmcnt(0)
	s_add_u32 s8, s10, 0x700
	s_addc_u32 s9, s11, 0
	v_mov_b32_e32 v0, v90
	v_lshl_add_u64 v[94:95], s[8:9], 0, v[0:1]
	s_add_i32 s8, s12, 0x1000
	s_mov_b32 m0, s8
	s_nop 0
	global_load_lds_dwordx4 v[94:95], off
	s_add_u32 s8, s10, 0x2700
	s_addc_u32 s9, s11, 0
	v_mov_b32_e32 v0, v91
	v_lshl_add_u64 v[94:95], s[8:9], 0, v[0:1]
	s_add_i32 s8, s12, 0x1400
	s_mov_b32 m0, s8
	s_nop 0
	global_load_lds_dwordx4 v[94:95], off
	s_add_u32 s8, s10, 0x4700
	s_addc_u32 s9, s11, 0
	v_mov_b32_e32 v0, v92
	v_lshl_add_u64 v[94:95], s[8:9], 0, v[0:1]
	s_add_i32 s8, s12, 0x1800
	s_mov_b32 m0, s8
	s_nop 0
	global_load_lds_dwordx4 v[94:95], off
	s_add_u32 s8, s10, 0x6700
	s_addc_u32 s9, s11, 0
	v_mov_b32_e32 v0, v93
	v_lshl_add_u64 v[94:95], s[8:9], 0, v[0:1]
	s_add_i32 s8, s12, 0x1c00
	s_mov_b32 m0, s8
	s_nop 0
	global_load_lds_dwordx4 v[94:95], off
	v_mfma_f32_16x16x32_bf16 v[2:5], v[42:45], v[74:77], v[2:5]
	v_mfma_f32_16x16x32_bf16 v[2:5], v[46:49], v[78:81], v[2:5]
	v_mfma_f32_16x16x32_bf16 v[2:5], v[50:53], v[82:85], v[2:5]
	v_mfma_f32_16x16x32_bf16 v[2:5], v[54:57], v[86:89], v[2:5]
	s_waitcnt vmcnt(4)
	ds_read_b128 v[74:77], v34 offset:0
	ds_read_b128 v[42:45], v38 offset:1536
	ds_read_b128 v[78:81], v35 offset:0
	ds_read_b128 v[46:49], v39 offset:1536
	ds_read_b128 v[82:85], v36 offset:0
	ds_read_b128 v[50:53], v40 offset:1536
	ds_read_b128 v[86:89], v37 offset:0
	ds_read_b128 v[54:57], v41 offset:1536
	s_waitcnt lgkmcnt(0)
	v_mfma_f32_16x16x32_bf16 v[2:5], v[42:45], v[74:77], v[2:5]
	v_mfma_f32_16x16x32_bf16 v[2:5], v[46:49], v[78:81], v[2:5]
	v_mfma_f32_16x16x32_bf16 v[2:5], v[50:53], v[82:85], v[2:5]
	v_mfma_f32_16x16x32_bf16 v[2:5], v[54:57], v[86:89], v[2:5]
	s_waitcnt vmcnt(0)
	ds_read_b128 v[74:77], v34 offset:4096
	ds_read_b128 v[42:45], v38 offset:1792
	ds_read_b128 v[78:81], v35 offset:4096
	ds_read_b128 v[46:49], v39 offset:1792
	ds_read_b128 v[82:85], v36 offset:4096
	ds_read_b128 v[50:53], v40 offset:1792
	ds_read_b128 v[86:89], v37 offset:4096
	ds_read_b128 v[54:57], v41 offset:1792
	s_waitcnt lgkmcnt(0)
	v_mfma_f32_16x16x32_bf16 v[2:5], v[42:45], v[74:77], v[2:5]
	v_mfma_f32_16x16x32_bf16 v[2:5], v[46:49], v[78:81], v[2:5]
	v_mfma_f32_16x16x32_bf16 v[2:5], v[50:53], v[82:85], v[2:5]
	v_mfma_f32_16x16x32_bf16 v[2:5], v[54:57], v[86:89], v[2:5]
	s_mov_b32 m0, s13
	s_barrier
	s_and_saveexec_b64 s[0:1], s[36:37]
	s_cbranch_execz .LBB0_484
	v_lshl_add_u32 v0, s4, 7, v25
	v_or_b32_e32 v18, v0, v24
	v_ashrrev_i32_e32 v19, 31, v18
	v_lshlrev_b64 v[18:19], 6, v[18:19]
	v_lshl_add_u64 v[22:23], s[30:31], 0, v[18:19]
	global_load_dwordx4 v[18:21], v[22:23], off offset:48
	global_load_dwordx4 v[30:33], v[22:23], off offset:32
	global_load_dwordx4 v[34:37], v[22:23], off offset:16
	global_load_dwordx4 v[38:41], v[22:23], off
	s_movk_i32 s6, 0xfff
	s_mov_b32 s8, 0x42ce8ed0
	s_mov_b32 s9, 0xc2b17218
	s_mov_b32 s11, 0x3f2aaaab
	s_mov_b32 s12, 0x3f317218
	s_mov_b32 s10, 0x7f800000
	s_mov_b32 s13, 0x33800000
	s_waitcnt vmcnt(2)
	v_add_f32_e32 v30, v30, v31
	v_add_f32_e32 v32, v32, v33
	s_waitcnt vmcnt(0)
	v_mov_b32_e32 v22, v39
	v_mov_b32_e32 v23, v40
	v_mov_b32_e32 v39, v41
	v_pk_add_f32 v[22:23], v[22:23], v[38:39]
	v_mov_b32_e32 v38, v35
	v_mov_b32_e32 v39, v36
	v_mov_b32_e32 v35, v37
	v_pk_add_f32 v[34:35], v[38:39], v[34:35]
	v_pk_add_f32 v[22:23], v[22:23], v[22:23] op_sel:[0,1] op_sel_hi:[1,0]
	v_pk_add_f32 v[34:35], v[34:35], v[34:35] op_sel:[0,1] op_sel_hi:[1,0]
	v_mov_b32_e32 v23, v18
	v_mov_b32_e32 v35, v19
	v_mov_b32_e32 v31, v20
	v_mov_b32_e32 v33, v21
	v_pk_add_f32 v[18:19], v[22:23], v[34:35]
	v_pk_add_f32 v[20:21], v[30:31], v[32:33]
	s_nop 0
	v_pk_add_f32 v[18:19], v[18:19], v[20:21]
	s_nop 0
	v_add_f32_e32 v7, v18, v19
	v_fmamk_f32 v7, v7, 0x3a800000, v214
	v_bitop3_b32 v18, v0, s6, v24 bitop3:0xc8
	v_ashrrev_i32_e32 v0, 9, v0
	v_readlane_b32 s6, v252, 20
	v_rsq_f32_e32 v15, v7
	v_and_b32_e32 v7, -8, v0
	v_lshlrev_b32_e32 v0, 2, v18
	v_readlane_b32 s7, v252, 21
	s_nop 1
	v_lshl_add_u64 v[18:19], s[6:7], 0, v[0:1]
	global_load_dword v0, v[8:9], off
	s_mov_b32 s6, 0xbfb8aa3b
	s_mov_b32 s7, 0xb2a5705f
	s_waitcnt vmcnt(0)
	v_fmac_f32_e32 v0, v2, v15
	v_mul_f32_e64 v20, |v0|, s6
	v_fma_f32 v21, |v0|, s6, -v20
	v_rndne_f32_e32 v22, v20
	v_fma_f32 v21, |v0|, s7, v21
	v_sub_f32_e32 v20, v20, v22
	v_add_f32_e32 v20, v20, v21
	v_exp_f32_e32 v20, v20
	v_cvt_i32_f32_e32 v21, v22
	v_cmp_ngt_f32_e64 vcc, |v0|, s8
	v_min_f32_e32 v2, 0, v0
	v_ldexp_f32 v20, v20, v21
	v_cndmask_b32_e32 v20, 0, v20, vcc
	v_cmp_nlt_f32_e64 vcc, |v0|, s9
	s_nop 1
	v_cndmask_b32_e32 v0, v223, v20, vcc
	v_add_f32_e32 v22, 1.0, v0
	v_add_f32_e32 v20, -1.0, v22
	v_sub_f32_e32 v21, v20, v22
	v_add_f32_e32 v21, 1.0, v21
	v_sub_f32_e32 v20, v0, v20
	v_add_f32_e32 v23, v20, v21
	v_frexp_mant_f32_e32 v20, v22
	v_cmp_gt_f32_e32 vcc, s11, v20
	v_cvt_f64_f32_e32 v[20:21], v22
	v_frexp_exp_i32_f64_e32 v20, v[20:21]
	v_subbrev_co_u32_e32 v20, vcc, 0, v20, vcc
	v_sub_u32_e32 v21, 0, v20
	v_ldexp_f32 v22, v22, v21
	v_ldexp_f32 v21, v23, v21
	v_add_f32_e32 v23, -1.0, v22
	v_add_f32_e32 v29, 1.0, v23
	v_sub_f32_e32 v29, v22, v29
	v_add_f32_e32 v29, v21, v29
	v_add_f32_e32 v30, v23, v29
	v_sub_f32_e32 v23, v23, v30
	v_add_f32_e32 v23, v29, v23
	v_add_f32_e32 v29, 1.0, v22
	v_add_f32_e32 v31, -1.0, v29
	v_sub_f32_e32 v22, v22, v31
	v_add_f32_e32 v21, v21, v22
	v_add_f32_e32 v22, v29, v21
	v_sub_f32_e32 v29, v29, v22
	v_add_f32_e32 v21, v21, v29
	v_rcp_f32_e32 v29, v22
	v_cvt_f32_i32_e32 v20, v20
	v_cmp_neq_f32_e32 vcc, s10, v0
	v_mul_f32_e32 v31, v30, v29
	v_mul_f32_e32 v32, v22, v31
	v_fma_f32 v33, v31, v22, -v32
	v_fmac_f32_e32 v33, v31, v21
	v_add_f32_e32 v34, v32, v33
	v_sub_f32_e32 v35, v30, v34
	v_sub_f32_e32 v30, v30, v35
	v_sub_f32_e32 v32, v34, v32
	v_sub_f32_e32 v30, v30, v34
	v_add_f32_e32 v23, v23, v30
	v_sub_f32_e32 v30, v32, v33
	v_add_f32_e32 v23, v30, v23
	v_add_f32_e32 v30, v35, v23
	v_mul_f32_e32 v32, v29, v30
	v_mul_f32_e32 v33, v22, v32
	v_fma_f32 v22, v32, v22, -v33
	v_fmac_f32_e32 v22, v32, v21
	v_sub_f32_e32 v21, v35, v30
	v_add_f32_e32 v21, v23, v21
	v_add_f32_e32 v23, v33, v22
	v_sub_f32_e32 v34, v30, v23
	v_sub_f32_e32 v30, v30, v34
	v_sub_f32_e32 v33, v23, v33
	v_sub_f32_e32 v23, v30, v23
	v_add_f32_e32 v21, v21, v23
	v_sub_f32_e32 v22, v33, v22
	v_add_f32_e32 v21, v22, v21
	v_add_f32_e32 v22, v31, v32
	v_add_f32_e32 v21, v34, v21
	v_sub_f32_e32 v23, v22, v31
	v_mul_f32_e32 v21, v29, v21
	v_sub_f32_e32 v23, v32, v23
	v_add_f32_e32 v21, v23, v21
	v_mul_f32_e32 v31, 0x3f317218, v20
	v_add_f32_e32 v23, v22, v21
	v_fma_f32 v32, v20, s12, -v31
	v_mul_f32_e32 v29, v23, v23
	v_fmac_f32_e32 v32, 0xb102e308, v20
	v_sub_f32_e32 v20, v23, v22
	v_fmamk_f32 v30, v29, 0x3e9b6dac, v215
	v_sub_f32_e32 v20, v21, v20
	v_add_f32_e32 v21, v31, v32
	v_fmaak_f32 v30, v29, v30, 0x3f2aaada
	v_sub_f32_e32 v22, v21, v31
	v_ldexp_f32 v31, v23, 1
	v_mul_f32_e32 v23, v23, v29
	v_mul_f32_e32 v23, v23, v30
	v_add_f32_e32 v29, v31, v23
	v_sub_f32_e32 v30, v29, v31
	v_ldexp_f32 v20, v20, 1
	v_sub_f32_e32 v23, v23, v30
	v_add_f32_e32 v20, v20, v23
	v_add_f32_e32 v23, v29, v20
	v_sub_f32_e32 v29, v23, v29
	v_sub_f32_e32 v20, v20, v29
	v_add_f32_e32 v29, v21, v23
	v_sub_f32_e32 v30, v29, v21
	v_sub_f32_e32 v31, v29, v30
	v_sub_f32_e32 v22, v32, v22
	v_sub_f32_e32 v21, v21, v31
	v_sub_f32_e32 v23, v23, v30
	v_add_f32_e32 v21, v23, v21
	v_add_f32_e32 v23, v22, v20
	v_sub_f32_e32 v30, v23, v22
	v_sub_f32_e32 v31, v23, v30
	v_sub_f32_e32 v22, v22, v31
	v_sub_f32_e32 v20, v20, v30
	v_add_f32_e32 v21, v23, v21
	v_add_f32_e32 v20, v20, v22
	v_add_f32_e32 v22, v29, v21
	v_sub_f32_e32 v23, v22, v29
	v_sub_f32_e32 v21, v21, v23
	v_add_f32_e32 v20, v20, v21
	v_add_f32_e32 v20, v22, v20
	v_cndmask_b32_e32 v20, v223, v20, vcc
	v_cmp_lt_f32_e64 vcc, |v0|, s13
	s_nop 1
	v_cndmask_b32_e32 v0, v20, v0, vcc
	v_or_b32_e32 v20, v7, v6
	v_ashrrev_i32_e32 v21, 31, v20
	v_lshlrev_b64 v[20:21], 14, v[20:21]
	v_sub_f32_e32 v0, v2, v0
	v_lshl_add_u64 v[20:21], v[18:19], 0, v[20:21]
	global_store_dword v[20:21], v0, off
	global_load_dword v0, v[10:11], off offset:4
	s_waitcnt vmcnt(0)
	v_fmac_f32_e32 v0, v3, v15
	v_mul_f32_e64 v2, |v0|, s6
	v_fma_f32 v3, |v0|, s6, -v2
	v_rndne_f32_e32 v21, v2
	v_fma_f32 v3, |v0|, s7, v3
	v_sub_f32_e32 v2, v2, v21
	v_add_f32_e32 v2, v2, v3
	v_exp_f32_e32 v2, v2
	v_cvt_i32_f32_e32 v3, v21
	v_cmp_ngt_f32_e64 vcc, |v0|, s8
	v_min_f32_e32 v20, 0, v0
	v_ldexp_f32 v2, v2, v3
	v_cndmask_b32_e32 v2, 0, v2, vcc
	v_cmp_nlt_f32_e64 vcc, |v0|, s9
	s_nop 1
	v_cndmask_b32_e32 v0, v223, v2, vcc
	v_add_f32_e32 v21, 1.0, v0
	v_add_f32_e32 v2, -1.0, v21
	v_sub_f32_e32 v3, v2, v21
	v_add_f32_e32 v3, 1.0, v3
	v_sub_f32_e32 v2, v0, v2
	v_add_f32_e32 v22, v2, v3
	v_frexp_mant_f32_e32 v2, v21
	v_cmp_gt_f32_e32 vcc, s11, v2
	v_cvt_f64_f32_e32 v[2:3], v21
	v_frexp_exp_i32_f64_e32 v2, v[2:3]
	v_subbrev_co_u32_e32 v2, vcc, 0, v2, vcc
	v_sub_u32_e32 v3, 0, v2
	v_ldexp_f32 v21, v21, v3
	v_ldexp_f32 v3, v22, v3
	v_add_f32_e32 v22, -1.0, v21
	v_add_f32_e32 v23, 1.0, v22
	v_sub_f32_e32 v23, v21, v23
	v_add_f32_e32 v23, v3, v23
	v_add_f32_e32 v29, v22, v23
	v_sub_f32_e32 v22, v22, v29
	v_add_f32_e32 v22, v23, v22
	v_add_f32_e32 v23, 1.0, v21
	v_add_f32_e32 v30, -1.0, v23
	v_sub_f32_e32 v21, v21, v30
	v_add_f32_e32 v3, v3, v21
	v_add_f32_e32 v21, v23, v3
	v_sub_f32_e32 v23, v23, v21
	v_add_f32_e32 v3, v3, v23
	v_rcp_f32_e32 v23, v21
	v_cvt_f32_i32_e32 v2, v2
	v_cmp_neq_f32_e32 vcc, s10, v0
	v_mul_f32_e32 v30, v29, v23
	v_mul_f32_e32 v31, v21, v30
	v_fma_f32 v32, v30, v21, -v31
	v_fmac_f32_e32 v32, v30, v3
	v_add_f32_e32 v33, v31, v32
	v_sub_f32_e32 v34, v29, v33
	v_sub_f32_e32 v29, v29, v34
	v_sub_f32_e32 v31, v33, v31
	v_sub_f32_e32 v29, v29, v33
	v_add_f32_e32 v22, v22, v29
	v_sub_f32_e32 v29, v31, v32
	v_add_f32_e32 v22, v29, v22
	v_add_f32_e32 v29, v34, v22
	v_mul_f32_e32 v31, v23, v29
	v_mul_f32_e32 v32, v21, v31
	v_fma_f32 v21, v31, v21, -v32
	v_fmac_f32_e32 v21, v31, v3
	v_sub_f32_e32 v3, v34, v29
	v_add_f32_e32 v3, v22, v3
	v_add_f32_e32 v22, v32, v21
	v_sub_f32_e32 v33, v29, v22
	v_sub_f32_e32 v29, v29, v33
	v_sub_f32_e32 v32, v22, v32
	v_sub_f32_e32 v22, v29, v22
	v_add_f32_e32 v3, v3, v22
	v_sub_f32_e32 v21, v32, v21
	v_add_f32_e32 v3, v21, v3
	v_add_f32_e32 v21, v30, v31
	v_add_f32_e32 v3, v33, v3
	v_sub_f32_e32 v22, v21, v30
	v_mul_f32_e32 v3, v23, v3
	v_sub_f32_e32 v22, v31, v22
	v_add_f32_e32 v3, v22, v3
	v_mul_f32_e32 v30, 0x3f317218, v2
	v_add_f32_e32 v22, v21, v3
	v_fma_f32 v31, v2, s12, -v30
	v_mul_f32_e32 v23, v22, v22
	v_fmac_f32_e32 v31, 0xb102e308, v2
	v_sub_f32_e32 v2, v22, v21
	v_fmamk_f32 v29, v23, 0x3e9b6dac, v215
	v_sub_f32_e32 v2, v3, v2
	v_add_f32_e32 v3, v30, v31
	v_fmaak_f32 v29, v23, v29, 0x3f2aaada
	v_sub_f32_e32 v21, v3, v30
	v_ldexp_f32 v30, v22, 1
	v_mul_f32_e32 v22, v22, v23
	v_mul_f32_e32 v22, v22, v29
	v_add_f32_e32 v23, v30, v22
	v_sub_f32_e32 v29, v23, v30
	v_ldexp_f32 v2, v2, 1
	v_sub_f32_e32 v22, v22, v29
	v_add_f32_e32 v2, v2, v22
	v_add_f32_e32 v22, v23, v2
	v_sub_f32_e32 v23, v22, v23
	v_sub_f32_e32 v2, v2, v23
	v_add_f32_e32 v23, v3, v22
	v_sub_f32_e32 v29, v23, v3
	v_sub_f32_e32 v30, v23, v29
	v_sub_f32_e32 v21, v31, v21
	v_sub_f32_e32 v3, v3, v30
	v_sub_f32_e32 v22, v22, v29
	v_add_f32_e32 v3, v22, v3
	v_add_f32_e32 v22, v21, v2
	v_sub_f32_e32 v29, v22, v21
	v_sub_f32_e32 v30, v22, v29
	v_sub_f32_e32 v21, v21, v30
	v_sub_f32_e32 v2, v2, v29
	v_add_f32_e32 v3, v22, v3
	v_add_f32_e32 v2, v2, v21
	v_add_f32_e32 v21, v23, v3
	v_sub_f32_e32 v22, v21, v23
	v_sub_f32_e32 v3, v3, v22
	v_add_f32_e32 v2, v2, v3
	v_add_f32_e32 v2, v21, v2
	v_cndmask_b32_e32 v2, v223, v2, vcc
	v_cmp_lt_f32_e64 vcc, |v0|, s13
	s_nop 1
	v_cndmask_b32_e32 v0, v2, v0, vcc
	v_or_b32_e32 v2, v7, v26
	v_ashrrev_i32_e32 v3, 31, v2
	v_lshlrev_b64 v[2:3], 14, v[2:3]
	v_sub_f32_e32 v0, v20, v0
	v_lshl_add_u64 v[2:3], v[18:19], 0, v[2:3]
	global_store_dword v[2:3], v0, off
	global_load_dword v0, v[10:11], off offset:8
	s_waitcnt vmcnt(0)
	v_fmac_f32_e32 v0, v4, v15
	v_mul_f32_e64 v2, |v0|, s6
	v_fma_f32 v3, |v0|, s6, -v2
	v_rndne_f32_e32 v20, v2
	v_fma_f32 v3, |v0|, s7, v3
	v_sub_f32_e32 v2, v2, v20
	v_add_f32_e32 v2, v2, v3
	v_exp_f32_e32 v2, v2
	v_cvt_i32_f32_e32 v3, v20
	v_cmp_ngt_f32_e64 vcc, |v0|, s8
	v_min_f32_e32 v4, 0, v0
	v_ldexp_f32 v2, v2, v3
	v_cndmask_b32_e32 v2, 0, v2, vcc
	v_cmp_nlt_f32_e64 vcc, |v0|, s9
	s_nop 1
	v_cndmask_b32_e32 v0, v223, v2, vcc
	v_add_f32_e32 v20, 1.0, v0
	v_add_f32_e32 v2, -1.0, v20
	v_sub_f32_e32 v3, v2, v20
	v_add_f32_e32 v3, 1.0, v3
	v_sub_f32_e32 v2, v0, v2
	v_add_f32_e32 v21, v2, v3
	v_frexp_mant_f32_e32 v2, v20
	v_cmp_gt_f32_e32 vcc, s11, v2
	v_cvt_f64_f32_e32 v[2:3], v20
	v_frexp_exp_i32_f64_e32 v2, v[2:3]
	v_subbrev_co_u32_e32 v2, vcc, 0, v2, vcc
	v_sub_u32_e32 v3, 0, v2
	v_ldexp_f32 v20, v20, v3
	v_ldexp_f32 v3, v21, v3
	v_add_f32_e32 v21, -1.0, v20
	v_add_f32_e32 v22, 1.0, v21
	v_sub_f32_e32 v22, v20, v22
	v_add_f32_e32 v22, v3, v22
	v_add_f32_e32 v23, v21, v22
	v_sub_f32_e32 v21, v21, v23
	v_add_f32_e32 v21, v22, v21
	v_add_f32_e32 v22, 1.0, v20
	v_add_f32_e32 v29, -1.0, v22
	v_sub_f32_e32 v20, v20, v29
	v_add_f32_e32 v3, v3, v20
	v_add_f32_e32 v20, v22, v3
	v_sub_f32_e32 v22, v22, v20
	v_add_f32_e32 v3, v3, v22
	v_rcp_f32_e32 v22, v20
	v_cvt_f32_i32_e32 v2, v2
	v_cmp_neq_f32_e32 vcc, s10, v0
	v_mul_f32_e32 v29, v23, v22
	v_mul_f32_e32 v30, v20, v29
	v_fma_f32 v31, v29, v20, -v30
	v_fmac_f32_e32 v31, v29, v3
	v_add_f32_e32 v32, v30, v31
	v_sub_f32_e32 v33, v23, v32
	v_sub_f32_e32 v23, v23, v33
	v_sub_f32_e32 v30, v32, v30
	v_sub_f32_e32 v23, v23, v32
	v_add_f32_e32 v21, v21, v23
	v_sub_f32_e32 v23, v30, v31
	v_add_f32_e32 v21, v23, v21
	v_add_f32_e32 v23, v33, v21
	v_mul_f32_e32 v30, v22, v23
	v_mul_f32_e32 v31, v20, v30
	v_fma_f32 v20, v30, v20, -v31
	v_fmac_f32_e32 v20, v30, v3
	v_sub_f32_e32 v3, v33, v23
	v_add_f32_e32 v3, v21, v3
	v_add_f32_e32 v21, v31, v20
	v_sub_f32_e32 v32, v23, v21
	v_sub_f32_e32 v23, v23, v32
	v_sub_f32_e32 v31, v21, v31
	v_sub_f32_e32 v21, v23, v21
	v_add_f32_e32 v3, v3, v21
	v_sub_f32_e32 v20, v31, v20
	v_add_f32_e32 v3, v20, v3
	v_add_f32_e32 v20, v29, v30
	v_add_f32_e32 v3, v32, v3
	v_sub_f32_e32 v21, v20, v29
	v_mul_f32_e32 v3, v22, v3
	v_sub_f32_e32 v21, v30, v21
	v_add_f32_e32 v3, v21, v3
	v_mul_f32_e32 v29, 0x3f317218, v2
	v_add_f32_e32 v21, v20, v3
	v_fma_f32 v30, v2, s12, -v29
	v_mul_f32_e32 v22, v21, v21
	v_fmac_f32_e32 v30, 0xb102e308, v2
	v_sub_f32_e32 v2, v21, v20
	v_fmamk_f32 v23, v22, 0x3e9b6dac, v215
	v_sub_f32_e32 v2, v3, v2
	v_add_f32_e32 v3, v29, v30
	v_fmaak_f32 v23, v22, v23, 0x3f2aaada
	v_sub_f32_e32 v20, v3, v29
	v_ldexp_f32 v29, v21, 1
	v_mul_f32_e32 v21, v21, v22
	v_mul_f32_e32 v21, v21, v23
	v_add_f32_e32 v22, v29, v21
	v_sub_f32_e32 v23, v22, v29
	v_ldexp_f32 v2, v2, 1
	v_sub_f32_e32 v21, v21, v23
	v_add_f32_e32 v2, v2, v21
	v_add_f32_e32 v21, v22, v2
	v_sub_f32_e32 v22, v21, v22
	v_sub_f32_e32 v2, v2, v22
	v_add_f32_e32 v22, v3, v21
	v_sub_f32_e32 v23, v22, v3
	v_sub_f32_e32 v29, v22, v23
	v_sub_f32_e32 v20, v30, v20
	v_sub_f32_e32 v3, v3, v29
	v_sub_f32_e32 v21, v21, v23
	v_add_f32_e32 v3, v21, v3
	v_add_f32_e32 v21, v20, v2
	v_sub_f32_e32 v23, v21, v20
	v_sub_f32_e32 v29, v21, v23
	v_sub_f32_e32 v20, v20, v29
	v_sub_f32_e32 v2, v2, v23
	v_add_f32_e32 v3, v21, v3
	v_add_f32_e32 v2, v2, v20
	v_add_f32_e32 v20, v22, v3
	v_sub_f32_e32 v21, v20, v22
	v_sub_f32_e32 v3, v3, v21
	v_add_f32_e32 v2, v2, v3
	v_add_f32_e32 v2, v20, v2
	v_cndmask_b32_e32 v2, v223, v2, vcc
	v_cmp_lt_f32_e64 vcc, |v0|, s13
	s_nop 1
	v_cndmask_b32_e32 v0, v2, v0, vcc
	v_or_b32_e32 v2, v7, v27
	v_ashrrev_i32_e32 v3, 31, v2
	v_lshlrev_b64 v[2:3], 14, v[2:3]
	v_sub_f32_e32 v0, v4, v0
	v_lshl_add_u64 v[2:3], v[18:19], 0, v[2:3]
	global_store_dword v[2:3], v0, off
	global_load_dword v0, v[10:11], off offset:12
	s_waitcnt vmcnt(0)
	v_fmac_f32_e32 v0, v5, v15
	v_mul_f32_e64 v2, |v0|, s6
	v_fma_f32 v3, |v0|, s6, -v2
	v_rndne_f32_e32 v5, v2
	v_fma_f32 v3, |v0|, s7, v3
	v_sub_f32_e32 v2, v2, v5
	v_add_f32_e32 v2, v2, v3
	v_exp_f32_e32 v2, v2
	v_cvt_i32_f32_e32 v3, v5
	v_cmp_ngt_f32_e64 vcc, |v0|, s8
	v_min_f32_e32 v4, 0, v0
	v_ldexp_f32 v2, v2, v3
	v_cndmask_b32_e32 v2, 0, v2, vcc
	v_cmp_nlt_f32_e64 vcc, |v0|, s9
	s_nop 1
	v_cndmask_b32_e32 v0, v223, v2, vcc
	v_add_f32_e32 v5, 1.0, v0
	v_add_f32_e32 v2, -1.0, v5
	v_sub_f32_e32 v3, v2, v5
	v_add_f32_e32 v3, 1.0, v3
	v_sub_f32_e32 v2, v0, v2
	v_add_f32_e32 v15, v2, v3
	v_frexp_mant_f32_e32 v2, v5
	v_cmp_gt_f32_e32 vcc, s11, v2
	v_cvt_f64_f32_e32 v[2:3], v5
	v_frexp_exp_i32_f64_e32 v2, v[2:3]
	v_subbrev_co_u32_e32 v2, vcc, 0, v2, vcc
	v_sub_u32_e32 v3, 0, v2
	v_ldexp_f32 v5, v5, v3
	v_ldexp_f32 v3, v15, v3
	v_add_f32_e32 v15, -1.0, v5
	v_add_f32_e32 v20, 1.0, v15
	v_sub_f32_e32 v20, v5, v20
	v_add_f32_e32 v20, v3, v20
	v_add_f32_e32 v21, v15, v20
	v_sub_f32_e32 v15, v15, v21
	v_add_f32_e32 v15, v20, v15
	v_add_f32_e32 v20, 1.0, v5
	v_add_f32_e32 v22, -1.0, v20
	v_sub_f32_e32 v5, v5, v22
	v_add_f32_e32 v3, v3, v5
	v_add_f32_e32 v5, v20, v3
	v_sub_f32_e32 v20, v20, v5
	v_add_f32_e32 v3, v3, v20
	v_rcp_f32_e32 v20, v5
	v_cvt_f32_i32_e32 v2, v2
	v_cmp_neq_f32_e32 vcc, s10, v0
	v_mul_f32_e32 v22, v21, v20
	v_mul_f32_e32 v23, v5, v22
	v_fma_f32 v29, v22, v5, -v23
	v_fmac_f32_e32 v29, v22, v3
	v_add_f32_e32 v30, v23, v29
	v_sub_f32_e32 v31, v21, v30
	v_sub_f32_e32 v21, v21, v31
	v_sub_f32_e32 v23, v30, v23
	v_sub_f32_e32 v21, v21, v30
	v_add_f32_e32 v15, v15, v21
	v_sub_f32_e32 v21, v23, v29
	v_add_f32_e32 v15, v21, v15
	v_add_f32_e32 v21, v31, v15
	v_mul_f32_e32 v23, v20, v21
	v_mul_f32_e32 v29, v5, v23
	v_fma_f32 v5, v23, v5, -v29
	v_fmac_f32_e32 v5, v23, v3
	v_sub_f32_e32 v3, v31, v21
	v_add_f32_e32 v3, v15, v3
	v_add_f32_e32 v15, v29, v5
	v_sub_f32_e32 v30, v21, v15
	v_sub_f32_e32 v21, v21, v30
	v_sub_f32_e32 v29, v15, v29
	v_sub_f32_e32 v15, v21, v15
	v_add_f32_e32 v3, v3, v15
	v_sub_f32_e32 v5, v29, v5
	v_add_f32_e32 v3, v5, v3
	v_add_f32_e32 v5, v22, v23
	v_add_f32_e32 v3, v30, v3
	v_sub_f32_e32 v15, v5, v22
	v_mul_f32_e32 v3, v20, v3
	v_sub_f32_e32 v15, v23, v15
	v_add_f32_e32 v3, v15, v3
	v_mul_f32_e32 v22, 0x3f317218, v2
	v_add_f32_e32 v15, v5, v3
	v_fma_f32 v23, v2, s12, -v22
	v_mul_f32_e32 v20, v15, v15
	v_fmac_f32_e32 v23, 0xb102e308, v2
	v_sub_f32_e32 v2, v15, v5
	v_fmamk_f32 v21, v20, 0x3e9b6dac, v215
	v_sub_f32_e32 v2, v3, v2
	v_add_f32_e32 v3, v22, v23
	v_fmaak_f32 v21, v20, v21, 0x3f2aaada
	v_sub_f32_e32 v5, v3, v22
	v_ldexp_f32 v22, v15, 1
	v_mul_f32_e32 v15, v15, v20
	v_mul_f32_e32 v15, v15, v21
	v_add_f32_e32 v20, v22, v15
	v_sub_f32_e32 v21, v20, v22
	v_ldexp_f32 v2, v2, 1
	v_sub_f32_e32 v15, v15, v21
	v_add_f32_e32 v2, v2, v15
	v_add_f32_e32 v15, v20, v2
	v_sub_f32_e32 v20, v15, v20
	v_sub_f32_e32 v2, v2, v20
	v_add_f32_e32 v20, v3, v15
	v_sub_f32_e32 v21, v20, v3
	v_sub_f32_e32 v22, v20, v21
	v_sub_f32_e32 v5, v23, v5
	v_sub_f32_e32 v3, v3, v22
	v_sub_f32_e32 v15, v15, v21
	v_add_f32_e32 v3, v15, v3
	v_add_f32_e32 v15, v5, v2
	v_sub_f32_e32 v21, v15, v5
	v_sub_f32_e32 v22, v15, v21
	v_sub_f32_e32 v5, v5, v22
	v_sub_f32_e32 v2, v2, v21
	v_add_f32_e32 v3, v15, v3
	v_add_f32_e32 v2, v2, v5
	v_add_f32_e32 v5, v20, v3
	v_sub_f32_e32 v15, v5, v20
	v_sub_f32_e32 v3, v3, v15
	v_add_f32_e32 v2, v2, v3
	v_add_f32_e32 v2, v5, v2
	v_cndmask_b32_e32 v2, v223, v2, vcc
	v_cmp_lt_f32_e64 vcc, |v0|, s13
	s_nop 1
	v_cndmask_b32_e32 v0, v2, v0, vcc
	v_or_b32_e32 v2, v7, v28
	v_ashrrev_i32_e32 v3, 31, v2
	v_lshlrev_b64 v[2:3], 14, v[2:3]
	v_sub_f32_e32 v0, v4, v0
	v_lshl_add_u64 v[2:3], v[18:19], 0, v[2:3]
	global_store_dword v[2:3], v0, off
	s_branch .LBB0_484
